# prep: SSD depthwise conv+silu section rewritten by hand as a sliding window (16 consecutive tokens per thread, one new row load per token, scalar-base addressing); conv-loop wait moved to first consum
# speedup vs baseline: 1.0223x; 1.0058x over previous
; #define LAS __attribute__((address_space(3)))
; __device__ __forceinline__ float softplus(float x) { return fmaxf(x, 0.f) + __logf(1.0f + __expf(-fabsf(x))); }
; __device__ __forceinline__ f32x4 mfma16(bf16x8 a, bf16x8 b, f32x4 c) { return __builtin_amdgcn_mfma_f32_16x16x32_bf16(a, b, c, 0, 0, 0); }
; __device__ __forceinline__ void prep_tile64(LAS unsigned char* lds, const Params& P, const MixBufs& B, const bf16_t* sw, int layer, int L, int tile) {
;     ...
; #pragma unroll 1
;     for (int d = 0; d < 2; ++d) {
;         const int c = w * 16 + r;
;         const float bias = P.in[6][(layer * 2 + d) * 128 + c];
;         const bf16x8 b0 = *(const bf16x8*)(sw + 98304 + d * 4096 + (size_t)(w * 16 + r) * 32 + q * 8);
; #pragma unroll
;         for (int tm = 0; tm < 4; ++tm) {
;             f32x4 acc = (f32x4){0.f, 0.f, 0.f, 0.f};
;             acc = mfma16(*(const LAS bf16x8*)(gin + (tm * 16 + r) * 40 + q * 8), b0, acc);
; #pragma unroll
;             for (int jj = 0; jj < 4; ++jj) B.gla_la[((size_t)d * TG + t0 + tm * 16 + q * 4 + jj) * 128 + c] = -softplus(-(acc[jj] + bias)) * (1.0f / 16.0f);
;         }
;     }
.LBB0_295:
	v_lshl_add_u32 v18, s6, 7, v28
	v_ashrrev_i32_e32 v19, 31, v18
	v_cndmask_b32_e64 v0, 0, 1, s[0:1]
	s_lshl_b32 s84, s6, 13
	v_lshl_add_u64 v[18:19], v[18:19], 2, s[60:61]
	v_cmp_ne_u32_e32 vcc, 1, v0
	global_load_dword v0, v[18:19], off
	v_lshl_add_u64 v[18:19], v[22:23], 0, s[84:85]
	global_load_dwordx4 v[18:21], v[18:19], off
	s_lshl_b32 s0, s6, 15
	s_mov_b32 s1, s85
	v_lshl_add_u64 v[26:27], v[78:79], 0, s[0:1]
	v_lshlrev_b64 v[26:27], 9, v[26:27]
	s_and_b64 vcc, exec, vcc
	s_mov_b32 s6, 1
	s_waitcnt vmcnt(0) lgkmcnt(3)
	v_mfma_f32_16x16x32_bf16 v[30:33], v[2:5], v[18:21], 0
	s_nop 7
	v_add_f32_e32 v29, v0, v30
	v_max_f32_e64 v30, -v29, 0
	v_mul_f32_e64 v29, |v29|, s97
	v_exp_f32_e32 v29, v29
	s_nop 0
	v_add_f32_e32 v29, 1.0, v29
	v_cmp_gt_f32_e64 s[0:1], s3, v29
	s_nop 1
	v_cndmask_b32_e64 v34, 0, 32, s[0:1]
	v_ldexp_f32 v29, v29, v34
	v_log_f32_e32 v29, v29
	s_nop 0
	v_mul_f32_e32 v34, 0x3f317217, v29
	v_fma_f32 v34, v29, s66, -v34
	v_fmac_f32_e32 v34, 0x3377d1cf, v29
	v_fmac_f32_e32 v34, 0x3f317217, v29
	v_cmp_lt_f32_e64 s[42:43], |v29|, s67
	s_nop 1
	v_cndmask_b32_e64 v29, v29, v34, s[42:43]
	v_cndmask_b32_e64 v34, 0, v209, s[0:1]
	v_sub_f32_e32 v29, v29, v34
	v_add_f32_e32 v29, v30, v29
	v_mul_f32_e32 v29, 0xbd800000, v29
	v_lshl_add_u64 v[34:35], v[24:25], 0, v[26:27]
	global_store_dword v[34:35], v29, off
	v_add_f32_e32 v29, v0, v31
	v_max_f32_e64 v30, -v29, 0
	v_mul_f32_e64 v29, |v29|, s97
	v_exp_f32_e32 v29, v29
	s_nop 0
	v_add_f32_e32 v29, 1.0, v29
	v_cmp_gt_f32_e64 s[0:1], s3, v29
	s_nop 1
	v_cndmask_b32_e64 v31, 0, 32, s[0:1]
	v_ldexp_f32 v29, v29, v31
	v_log_f32_e32 v29, v29
	s_nop 0
	v_mul_f32_e32 v31, 0x3f317217, v29
	v_fma_f32 v31, v29, s66, -v31
	v_fmac_f32_e32 v31, 0x3377d1cf, v29
	v_fmac_f32_e32 v31, 0x3f317217, v29
	v_cmp_lt_f32_e64 s[42:43], |v29|, s67
	s_nop 1
	v_cndmask_b32_e64 v29, v29, v31, s[42:43]
	v_cndmask_b32_e64 v31, 0, v209, s[0:1]
	v_sub_f32_e32 v29, v29, v31
	v_add_f32_e32 v29, v30, v29
	v_mul_f32_e32 v29, 0xbd800000, v29
	global_store_dword v[34:35], v29, off offset:512
	v_add_f32_e32 v29, v0, v32
	v_max_f32_e64 v30, -v29, 0
	v_mul_f32_e64 v29, |v29|, s97
	v_exp_f32_e32 v29, v29
	s_nop 0
	v_add_f32_e32 v29, 1.0, v29
	v_cmp_gt_f32_e64 s[0:1], s3, v29
	s_nop 1
	v_cndmask_b32_e64 v31, 0, 32, s[0:1]
	v_ldexp_f32 v29, v29, v31
	v_log_f32_e32 v29, v29
	s_nop 0
	v_mul_f32_e32 v31, 0x3f317217, v29
	v_fma_f32 v31, v29, s66, -v31
	v_fmac_f32_e32 v31, 0x3377d1cf, v29
	v_fmac_f32_e32 v31, 0x3f317217, v29
	v_cmp_lt_f32_e64 s[42:43], |v29|, s67
	s_nop 1
	v_cndmask_b32_e64 v29, v29, v31, s[42:43]
	v_cndmask_b32_e64 v31, 0, v209, s[0:1]
	v_sub_f32_e32 v29, v29, v31
	v_add_f32_e32 v29, v30, v29
	v_mul_f32_e32 v29, 0xbd800000, v29
	global_store_dword v[34:35], v29, off offset:1024
	v_add_f32_e32 v29, v0, v33
	v_max_f32_e64 v30, -v29, 0
	v_mul_f32_e64 v29, |v29|, s97
	v_exp_f32_e32 v29, v29
	s_nop 0
	v_add_f32_e32 v29, 1.0, v29
	v_cmp_gt_f32_e64 s[0:1], s3, v29
	s_nop 1
	v_cndmask_b32_e64 v31, 0, 32, s[0:1]
	v_ldexp_f32 v29, v29, v31
	v_log_f32_e32 v29, v29
	s_nop 0
	v_mul_f32_e32 v31, 0x3f317217, v29
	v_fma_f32 v31, v29, s66, -v31
	v_fmac_f32_e32 v31, 0x3377d1cf, v29
	v_fmac_f32_e32 v31, 0x3f317217, v29
	v_cmp_lt_f32_e64 s[42:43], |v29|, s67
	s_nop 1
	v_cndmask_b32_e64 v29, v29, v31, s[42:43]
	v_cndmask_b32_e64 v31, 0, v209, s[0:1]
	v_sub_f32_e32 v29, v29, v31
	v_add_f32_e32 v29, v30, v29
	s_waitcnt lgkmcnt(2)
	v_mfma_f32_16x16x32_bf16 v[30:33], v[6:9], v[18:21], 0
	v_mul_f32_e32 v29, 0xbd800000, v29
	global_store_dword v[34:35], v29, off offset:1536
	v_mov_b32_e32 v35, v27
	s_nop 4
	v_add_f32_e32 v29, v0, v30
	v_max_f32_e64 v30, -v29, 0
	v_mul_f32_e64 v29, |v29|, s97
	v_exp_f32_e32 v29, v29
	s_nop 0
	v_add_f32_e32 v29, 1.0, v29
	v_cmp_gt_f32_e64 s[0:1], s3, v29
	s_nop 1
	v_cndmask_b32_e64 v34, 0, 32, s[0:1]
	v_ldexp_f32 v29, v29, v34
	v_log_f32_e32 v29, v29
	s_nop 0
	v_mul_f32_e32 v34, 0x3f317217, v29
	v_fma_f32 v34, v29, s66, -v34
	v_fmac_f32_e32 v34, 0x3377d1cf, v29
	v_fmac_f32_e32 v34, 0x3f317217, v29
	v_cmp_lt_f32_e64 s[42:43], |v29|, s67
	s_nop 1
	v_cndmask_b32_e64 v29, v29, v34, s[42:43]
	v_cndmask_b32_e64 v34, 0, v209, s[0:1]
	v_sub_f32_e32 v29, v29, v34
	v_add_f32_e32 v29, v30, v29
	v_or_b32_e32 v34, 0x2000, v26
	v_mul_f32_e32 v29, 0xbd800000, v29
	v_lshl_add_u64 v[34:35], v[24:25], 0, v[34:35]
	global_store_dword v[34:35], v29, off
	v_add_f32_e32 v29, v0, v31
	v_max_f32_e64 v30, -v29, 0
	v_mul_f32_e64 v29, |v29|, s97
	v_exp_f32_e32 v29, v29
	v_mov_b32_e32 v35, v27
	v_add_f32_e32 v29, 1.0, v29
	v_cmp_gt_f32_e64 s[0:1], s3, v29
	s_nop 1
	v_cndmask_b32_e64 v31, 0, 32, s[0:1]
	v_ldexp_f32 v29, v29, v31
	v_log_f32_e32 v29, v29
	s_nop 0
	v_mul_f32_e32 v31, 0x3f317217, v29
	v_fma_f32 v31, v29, s66, -v31
	v_fmac_f32_e32 v31, 0x3377d1cf, v29
	v_fmac_f32_e32 v31, 0x3f317217, v29
	v_cmp_lt_f32_e64 s[42:43], |v29|, s67
	s_nop 1
	v_cndmask_b32_e64 v29, v29, v31, s[42:43]
	v_cndmask_b32_e64 v31, 0, v209, s[0:1]
	v_sub_f32_e32 v29, v29, v31
	v_add_f32_e32 v29, v30, v29
	v_or_b32_e32 v30, 0x2200, v26
	v_mov_b32_e32 v31, v27
	v_mul_f32_e32 v29, 0xbd800000, v29
	v_lshl_add_u64 v[30:31], v[24:25], 0, v[30:31]
	global_store_dword v[30:31], v29, off
	v_add_f32_e32 v29, v0, v32
	v_max_f32_e64 v30, -v29, 0
	v_mul_f32_e64 v29, |v29|, s97
	v_exp_f32_e32 v29, v29
	s_nop 0
	v_add_f32_e32 v29, 1.0, v29
	v_cmp_gt_f32_e64 s[0:1], s3, v29
	s_nop 1
	v_cndmask_b32_e64 v31, 0, 32, s[0:1]
	v_ldexp_f32 v29, v29, v31
	v_log_f32_e32 v29, v29
	s_nop 0
	v_mul_f32_e32 v31, 0x3f317217, v29
	v_fma_f32 v31, v29, s66, -v31
	v_fmac_f32_e32 v31, 0x3377d1cf, v29
	v_fmac_f32_e32 v31, 0x3f317217, v29
	v_cmp_lt_f32_e64 s[42:43], |v29|, s67
	s_nop 1
	v_cndmask_b32_e64 v29, v29, v31, s[42:43]
	v_cndmask_b32_e64 v31, 0, v209, s[0:1]
	v_sub_f32_e32 v29, v29, v31
	v_add_f32_e32 v29, v30, v29
	v_or_b32_e32 v30, 0x2400, v26
	v_mov_b32_e32 v31, v27
	v_mul_f32_e32 v29, 0xbd800000, v29
	v_lshl_add_u64 v[30:31], v[24:25], 0, v[30:31]
	global_store_dword v[30:31], v29, off
	v_add_f32_e32 v29, v0, v33
	v_max_f32_e64 v30, -v29, 0
	v_mul_f32_e64 v29, |v29|, s97
	v_exp_f32_e32 v29, v29
	s_nop 0
	v_add_f32_e32 v29, 1.0, v29
	v_cmp_gt_f32_e64 s[0:1], s3, v29
	s_nop 1
	v_cndmask_b32_e64 v31, 0, 32, s[0:1]
	v_ldexp_f32 v29, v29, v31
	v_log_f32_e32 v29, v29
	s_nop 0
	v_mul_f32_e32 v31, 0x3f317217, v29
	v_fma_f32 v31, v29, s66, -v31
	v_fmac_f32_e32 v31, 0x3377d1cf, v29
	v_fmac_f32_e32 v31, 0x3f317217, v29
	v_cmp_lt_f32_e64 s[42:43], |v29|, s67
	s_nop 1
	v_cndmask_b32_e64 v29, v29, v31, s[42:43]
	v_cndmask_b32_e64 v31, 0, v209, s[0:1]
	v_sub_f32_e32 v29, v29, v31
	v_add_f32_e32 v29, v30, v29
	v_or_b32_e32 v30, 0x2600, v26
	v_mov_b32_e32 v31, v27
	v_mul_f32_e32 v29, 0xbd800000, v29
	v_lshl_add_u64 v[30:31], v[24:25], 0, v[30:31]
	global_store_dword v[30:31], v29, off
	s_waitcnt lgkmcnt(1)
; #define LAS __attribute__((address_space(3)))
; __device__ __forceinline__ float softplus(float x) { return fmaxf(x, 0.f) + __logf(1.0f + __expf(-fabsf(x))); }
; __device__ __forceinline__ f32x4 mfma16(bf16x8 a, bf16x8 b, f32x4 c) { return __builtin_amdgcn_mfma_f32_16x16x32_bf16(a, b, c, 0, 0, 0); }
; __device__ __forceinline__ void prep_tile64(LAS unsigned char* lds, const Params& P, const MixBufs& B, const bf16_t* sw, int layer, int L, int tile) {
;     ...
; #pragma unroll 1
;     for (int d = 0; d < 2; ++d) {
;         const int c = w * 16 + r;
;         const float bias = P.in[6][(layer * 2 + d) * 128 + c];
;         const bf16x8 b0 = *(const bf16x8*)(sw + 98304 + d * 4096 + (size_t)(w * 16 + r) * 32 + q * 8);
; #pragma unroll
;         for (int tm = 0; tm < 4; ++tm) {
;             f32x4 acc = (f32x4){0.f, 0.f, 0.f, 0.f};
;             acc = mfma16(*(const LAS bf16x8*)(gin + (tm * 16 + r) * 40 + q * 8), b0, acc);
; #pragma unroll
;             for (int jj = 0; jj < 4; ++jj) B.gla_la[((size_t)d * TG + t0 + tm * 16 + q * 4 + jj) * 128 + c] = -softplus(-(acc[jj] + bias)) * (1.0f / 16.0f);
;         }
;     }
	v_mfma_f32_16x16x32_bf16 v[30:33], v[10:13], v[18:21], 0
	s_waitcnt lgkmcnt(0)
	v_mfma_f32_16x16x32_bf16 v[18:21], v[14:17], v[18:21], 0
	s_nop 5
	v_add_f32_e32 v29, v0, v30
	v_max_f32_e64 v30, -v29, 0
	v_mul_f32_e64 v29, |v29|, s97
	v_exp_f32_e32 v29, v29
	v_add_f32_e32 v18, v0, v18
	v_add_f32_e32 v29, 1.0, v29
	v_cmp_gt_f32_e64 s[0:1], s3, v29
	s_nop 1
	v_cndmask_b32_e64 v34, 0, 32, s[0:1]
	v_ldexp_f32 v29, v29, v34
	v_log_f32_e32 v29, v29
	s_nop 0
	v_mul_f32_e32 v34, 0x3f317217, v29
	v_fma_f32 v34, v29, s66, -v34
	v_fmac_f32_e32 v34, 0x3377d1cf, v29
	v_fmac_f32_e32 v34, 0x3f317217, v29
	v_cmp_lt_f32_e64 s[42:43], |v29|, s67
	s_nop 1
	v_cndmask_b32_e64 v29, v29, v34, s[42:43]
	v_cndmask_b32_e64 v34, 0, v209, s[0:1]
	v_sub_f32_e32 v29, v29, v34
	v_add_f32_e32 v29, v30, v29
	v_or_b32_e32 v34, 0x4000, v26
	v_mul_f32_e32 v29, 0xbd800000, v29
	v_lshl_add_u64 v[34:35], v[24:25], 0, v[34:35]
	global_store_dword v[34:35], v29, off
	v_add_f32_e32 v29, v0, v31
	v_max_f32_e64 v30, -v29, 0
	v_mul_f32_e64 v29, |v29|, s97
	v_exp_f32_e32 v29, v29
	s_nop 0
	v_add_f32_e32 v29, 1.0, v29
	v_cmp_gt_f32_e64 s[0:1], s3, v29
	s_nop 1
	v_cndmask_b32_e64 v31, 0, 32, s[0:1]
	v_ldexp_f32 v29, v29, v31
	v_log_f32_e32 v29, v29
	s_nop 0
	v_mul_f32_e32 v31, 0x3f317217, v29
	v_fma_f32 v31, v29, s66, -v31
	v_fmac_f32_e32 v31, 0x3377d1cf, v29
	v_fmac_f32_e32 v31, 0x3f317217, v29
	v_cmp_lt_f32_e64 s[42:43], |v29|, s67
	s_nop 1
	v_cndmask_b32_e64 v29, v29, v31, s[42:43]
	v_cndmask_b32_e64 v31, 0, v209, s[0:1]
	v_sub_f32_e32 v29, v29, v31
	v_add_f32_e32 v29, v30, v29
	v_or_b32_e32 v30, 0x4200, v26
	v_mov_b32_e32 v31, v27
	v_mul_f32_e32 v29, 0xbd800000, v29
	v_lshl_add_u64 v[30:31], v[24:25], 0, v[30:31]
	global_store_dword v[30:31], v29, off
	v_add_f32_e32 v29, v0, v32
	v_max_f32_e64 v30, -v29, 0
	v_mul_f32_e64 v29, |v29|, s97
	v_exp_f32_e32 v29, v29
	s_nop 0
	v_add_f32_e32 v29, 1.0, v29
	v_cmp_gt_f32_e64 s[0:1], s3, v29
	s_nop 1
	v_cndmask_b32_e64 v31, 0, 32, s[0:1]
	v_ldexp_f32 v29, v29, v31
	v_log_f32_e32 v29, v29
	s_nop 0
	v_mul_f32_e32 v31, 0x3f317217, v29
	v_fma_f32 v31, v29, s66, -v31
	v_fmac_f32_e32 v31, 0x3377d1cf, v29
	v_fmac_f32_e32 v31, 0x3f317217, v29
	v_cmp_lt_f32_e64 s[42:43], |v29|, s67
	s_nop 1
	v_cndmask_b32_e64 v29, v29, v31, s[42:43]
	v_cndmask_b32_e64 v31, 0, v209, s[0:1]
	v_sub_f32_e32 v29, v29, v31
	v_add_f32_e32 v29, v30, v29
	v_or_b32_e32 v30, 0x4400, v26
	v_mov_b32_e32 v31, v27
	v_mul_f32_e32 v29, 0xbd800000, v29
	v_lshl_add_u64 v[30:31], v[24:25], 0, v[30:31]
	global_store_dword v[30:31], v29, off
	v_add_f32_e32 v29, v0, v33
	v_max_f32_e64 v30, -v29, 0
	v_mul_f32_e64 v29, |v29|, s97
	v_exp_f32_e32 v29, v29
	s_nop 0
	v_add_f32_e32 v29, 1.0, v29
	v_cmp_gt_f32_e64 s[0:1], s3, v29
	s_nop 1
	v_cndmask_b32_e64 v31, 0, 32, s[0:1]
	v_ldexp_f32 v29, v29, v31
	v_log_f32_e32 v29, v29
	s_nop 0
	v_mul_f32_e32 v31, 0x3f317217, v29
	v_fma_f32 v31, v29, s66, -v31
	v_fmac_f32_e32 v31, 0x3377d1cf, v29
	v_fmac_f32_e32 v31, 0x3f317217, v29
	v_cmp_lt_f32_e64 s[42:43], |v29|, s67
	s_nop 1
	v_cndmask_b32_e64 v29, v29, v31, s[42:43]
	v_cndmask_b32_e64 v31, 0, v209, s[0:1]
	v_sub_f32_e32 v29, v29, v31
	v_add_f32_e32 v29, v30, v29
	v_or_b32_e32 v30, 0x4600, v26
	v_mov_b32_e32 v31, v27
	v_mul_f32_e32 v29, 0xbd800000, v29
	v_lshl_add_u64 v[30:31], v[24:25], 0, v[30:31]
	global_store_dword v[30:31], v29, off
	v_max_f32_e64 v29, -v18, 0
	v_mul_f32_e64 v18, |v18|, s97
	v_exp_f32_e32 v18, v18
	v_mov_b32_e32 v31, v27
	v_add_f32_e32 v18, 1.0, v18
	v_cmp_gt_f32_e64 s[0:1], s3, v18
	s_nop 1
	v_cndmask_b32_e64 v30, 0, 32, s[0:1]
	v_ldexp_f32 v18, v18, v30
	v_log_f32_e32 v18, v18
	s_nop 0
	v_mul_f32_e32 v30, 0x3f317217, v18
	v_fma_f32 v30, v18, s66, -v30
	v_fmac_f32_e32 v30, 0x3377d1cf, v18
	v_fmac_f32_e32 v30, 0x3f317217, v18
	v_cmp_lt_f32_e64 s[42:43], |v18|, s67
	s_nop 1
	v_cndmask_b32_e64 v18, v18, v30, s[42:43]
	v_cndmask_b32_e64 v30, 0, v209, s[0:1]
	v_sub_f32_e32 v18, v18, v30
	v_add_f32_e32 v18, v29, v18
	v_or_b32_e32 v30, 0x6000, v26
	v_mul_f32_e32 v18, 0xbd800000, v18
	v_lshl_add_u64 v[30:31], v[24:25], 0, v[30:31]
	global_store_dword v[30:31], v18, off
	v_add_f32_e32 v18, v0, v19
	v_max_f32_e64 v19, -v18, 0
	v_mul_f32_e64 v18, |v18|, s97
	v_exp_f32_e32 v18, v18
	s_nop 0
	v_add_f32_e32 v18, 1.0, v18
	v_cmp_gt_f32_e64 s[0:1], s3, v18
	s_nop 1
	v_cndmask_b32_e64 v29, 0, 32, s[0:1]
	v_ldexp_f32 v18, v18, v29
	v_log_f32_e32 v18, v18
	s_nop 0
	v_mul_f32_e32 v29, 0x3f317217, v18
	v_fma_f32 v29, v18, s66, -v29
	v_fmac_f32_e32 v29, 0x3377d1cf, v18
	v_fmac_f32_e32 v29, 0x3f317217, v18
	v_cmp_lt_f32_e64 s[42:43], |v18|, s67
	s_nop 1
	v_cndmask_b32_e64 v18, v18, v29, s[42:43]
	v_cndmask_b32_e64 v29, 0, v209, s[0:1]
	v_sub_f32_e32 v18, v18, v29
	v_add_f32_e32 v18, v19, v18
	v_mul_f32_e32 v29, 0xbd800000, v18
	v_or_b32_e32 v18, 0x6200, v26
	v_mov_b32_e32 v19, v27
	v_lshl_add_u64 v[18:19], v[24:25], 0, v[18:19]
	global_store_dword v[18:19], v29, off
	v_add_f32_e32 v18, v0, v20
	v_max_f32_e64 v19, -v18, 0
	v_mul_f32_e64 v18, |v18|, s97
	v_exp_f32_e32 v18, v18
	v_add_f32_e32 v0, v0, v21
	v_add_f32_e32 v18, 1.0, v18
	v_cmp_gt_f32_e64 s[0:1], s3, v18
	s_nop 1
	v_cndmask_b32_e64 v20, 0, 32, s[0:1]
	v_ldexp_f32 v18, v18, v20
	v_log_f32_e32 v18, v18
	s_nop 0
	v_mul_f32_e32 v20, 0x3f317217, v18
	v_fma_f32 v20, v18, s66, -v20
	v_fmac_f32_e32 v20, 0x3377d1cf, v18
	v_fmac_f32_e32 v20, 0x3f317217, v18
	v_cmp_lt_f32_e64 s[42:43], |v18|, s67
	s_nop 1
	v_cndmask_b32_e64 v18, v18, v20, s[42:43]
	v_cndmask_b32_e64 v20, 0, v209, s[0:1]
	v_sub_f32_e32 v18, v18, v20
	v_add_f32_e32 v18, v19, v18
	v_mul_f32_e32 v20, 0xbd800000, v18
	v_or_b32_e32 v18, 0x6400, v26
	v_mov_b32_e32 v19, v27
	v_lshl_add_u64 v[18:19], v[24:25], 0, v[18:19]
	global_store_dword v[18:19], v20, off
	v_max_f32_e64 v18, -v0, 0
	v_mul_f32_e64 v0, |v0|, s97
	v_exp_f32_e32 v0, v0
	v_or_b32_e32 v26, 0x6600, v26
	v_add_f32_e32 v0, 1.0, v0
	v_cmp_gt_f32_e64 s[0:1], s3, v0
	s_nop 1
	v_cndmask_b32_e64 v19, 0, 32, s[0:1]
	v_ldexp_f32 v0, v0, v19
	v_log_f32_e32 v0, v0
	s_nop 0
	v_mul_f32_e32 v19, 0x3f317217, v0
	v_fma_f32 v19, v0, s66, -v19
	v_fmac_f32_e32 v19, 0x3377d1cf, v0
	v_fmac_f32_e32 v19, 0x3f317217, v0
	v_cmp_lt_f32_e64 s[42:43], |v0|, s67
	s_nop 1
	v_cndmask_b32_e64 v0, v0, v19, s[42:43]
	v_cndmask_b32_e64 v19, 0, v209, s[0:1]
	v_sub_f32_e32 v0, v0, v19
	v_add_f32_e32 v0, v18, v0
	v_mul_f32_e32 v0, 0xbd800000, v0
	v_lshl_add_u64 v[18:19], v[24:25], 0, v[26:27]
	s_mov_b64 s[0:1], 0
	global_store_dword v[18:19], v0, off
	s_cbranch_vccz .LBB0_295
; #define CONV_LOAD(dst, ii) do { const int t_ = (tid + 512 * (ii)) >> 7, tl_ = t0 + t_, pos_ = tl_ % L; \
;             _Pragma("unroll") for (int tap = 0; tap < 5; ++tap) { const int pp = pos_ + tap - 2; \
;                 dst[tap] = (pp >= 0 && pp < L) ? *(const u32x4*)(p + (size_t)(tl_ + tap - 2) * DINP + PC_XBC + c0) : (u32x4){0u, 0u, 0u, 0u}; } } while (0)
; __device__ __forceinline__ void prep_tile64(LAS unsigned char* lds, const Params& P, const MixBufs& B, const bf16_t* sw, int layer, int L, int tile) {
;     ...
;     {
;         const int c0 = (tid & 127) * 8;
;         float wt[5][8], bs[8];
;         { const f32x4 b0 = *(const f32x4*)(P.in[20] + layer * 1024 + c0), b1 = *(const f32x4*)(P.in[20] + layer * 1024 + c0 + 4);
;           bs[0] = b0[0]; bs[1] = b0[1]; bs[2] = b0[2]; bs[3] = b0[3]; bs[4] = b1[0]; bs[5] = b1[1]; bs[6] = b1[2]; bs[7] = b1[3]; }
; #pragma unroll
;         for (int tap = 0; tap < 5; ++tap) { const float* wp = P.in[19] + (size_t)(layer * 5 + tap) * 1024 + c0;
;             const f32x4 w0 = *(const f32x4*)wp, w1 = *(const f32x4*)(wp + 4);
;             wt[tap][0] = w0[0]; wt[tap][1] = w0[1]; wt[tap][2] = w0[2]; wt[tap][3] = w0[3]; wt[tap][4] = w1[0]; wt[tap][5] = w1[1]; wt[tap][6] = w1[2]; wt[tap][7] = w1[3]; }
;         u32x4 xr[5], xn[5];
;     ...
;         CONV_LOAD(xn, 0);
	v_lshlrev_b32_e32 v0, 3, v125
	v_and_b32_e32 v56, 0x3f8, v0
	v_lshlrev_b32_e32 v0, 2, v56
	v_lshl_add_u64 v[2:3], s[40:41], 0, v[0:1]
	v_add_co_u32_e32 v20, vcc, 0x1000, v2
	s_mov_b64 s[0:1], 0x1000
	s_nop 0
	v_addc_co_u32_e32 v21, vcc, 0, v3, vcc
	v_lshl_add_u64 v[24:25], v[2:3], 0, s[0:1]
	s_mov_b64 s[0:1], 0x2000
	v_add_co_u32_e32 v28, vcc, 0x2000, v2
	v_lshl_add_u64 v[32:33], v[2:3], 0, s[0:1]
	s_nop 0
	v_addc_co_u32_e32 v29, vcc, 0, v3, vcc
	s_mov_b64 s[0:1], 0x3000
	v_lshl_add_u64 v[40:41], v[2:3], 0, s[0:1]
	v_add_co_u32_e32 v36, vcc, 0x3000, v2
	s_mov_b64 s[0:1], 0x4000
	s_nop 0
	v_addc_co_u32_e32 v37, vcc, 0, v3, vcc
	v_lshl_add_u64 v[48:49], v[2:3], 0, s[0:1]
	s_movk_i32 s0, 0x4000
	v_add_co_u32_e32 v2, vcc, s0, v2
	global_load_dwordx4 v[4:7], v0, s[68:69] offset:16
	global_load_dwordx4 v[8:11], v0, s[68:69]
	v_addc_co_u32_e32 v3, vcc, 0, v3, vcc
	global_load_dwordx4 v[12:15], v0, s[40:41] offset:16
	global_load_dwordx4 v[16:19], v0, s[40:41]
	s_nop 0
	global_load_dwordx4 v[20:23], v[20:21], off
	s_nop 0
	global_load_dwordx4 v[24:27], v[24:25], off offset:16
	s_nop 0
	global_load_dwordx4 v[28:31], v[28:29], off
	s_nop 0
	global_load_dwordx4 v[32:35], v[32:33], off offset:16
	s_nop 0
	global_load_dwordx4 v[36:39], v[36:37], off
	s_nop 0
	global_load_dwordx4 v[40:43], v[40:41], off offset:16
	s_nop 0
	global_load_dwordx4 v[44:47], v[2:3], off
	s_nop 0
	global_load_dwordx4 v[48:51], v[48:49], off offset:16
	v_lshrrev_b32_e32 v52, 7, v125
	v_lshlrev_b32_e32 v52, 4, v52
	v_add_u32_e32 v53, s2, v52
	v_and_b32_e32 v92, 0x7f, v125
	v_lshlrev_b32_e32 v92, 4, v92
	v_mov_b32_e32 v93, v1
	v_add_u32_e32 v88, -2, v53
	s_nop 0
	v_mad_i64_i32 v[54:55], s[6:7], v88, s65, v[92:93]
	v_lshl_add_u64 v[54:55], s[92:93], 0, v[54:55]
	s_mov_b64 s[0:1], 0x1000
	v_lshl_add_u64 v[54:55], v[54:55], 0, s[0:1]
	s_mov_b64 s[6:7], 0x1c00
	global_load_dwordx4 v[56:59], v[54:55], off offset:832
	v_lshl_add_u64 v[54:55], v[54:55], 0, s[6:7]
	global_load_dwordx4 v[60:63], v[54:55], off offset:832
	v_lshl_add_u64 v[54:55], v[54:55], 0, s[6:7]
	global_load_dwordx4 v[64:67], v[54:55], off offset:832
	v_lshl_add_u64 v[54:55], v[54:55], 0, s[6:7]
	global_load_dwordx4 v[68:71], v[54:55], off offset:832
	v_lshl_add_u64 v[54:55], v[54:55], 0, s[6:7]
	global_load_dwordx4 v[72:75], v[54:55], off offset:832
	v_lshl_add_u64 v[54:55], v[54:55], 0, s[6:7]
	v_readlane_b32 s0, v251, 29
	v_readlane_b32 s1, v251, 30
	v_mov_b32_e32 v90, v53
	v_mov_b32_e32 v91, v1
	v_lshlrev_b64 v[90:91], 11, v[90:91]
	v_lshl_add_u64 v[94:95], s[0:1], 0, v[92:93]
	v_lshl_add_u64 v[94:95], v[94:95], 0, v[90:91]
	s_mov_b64 s[0:1], 0x800
	v_mov_b32_e32 v3, s36
	v_add_u32_e32 v3, -1, v3
	v_or_b32_e32 v2, v53, v3
	v_add_u32_e32 v0, 3, v53
	v_and_b32_e32 v88, v53, v3
	v_cmp_eq_u32_e32 vcc, 0, v88
	s_mov_b32 s5, 0
	s_waitcnt vmcnt(0)
	v_cndmask_b32_e32 v56, v56, v1, vcc
	v_cndmask_b32_e32 v57, v57, v1, vcc
	v_cndmask_b32_e32 v58, v58, v1, vcc
	v_cndmask_b32_e32 v59, v59, v1, vcc
	v_cndmask_b32_e32 v60, v60, v1, vcc
	v_cndmask_b32_e32 v61, v61, v1, vcc
	v_cndmask_b32_e32 v62, v62, v1, vcc
	v_cndmask_b32_e32 v63, v63, v1, vcc
; __device__ __forceinline__ unsigned pk2(float lo, float hi) { f32x2 f = {lo, hi}; bf16x2_t v = __builtin_convertvector(f, bf16x2_t); return __builtin_bit_cast(unsigned, v); }
; __device__ __forceinline__ float silu(float x) { return x * __builtin_amdgcn_rcpf(1.0f + __expf(-x)); }
; #define CONV_LOAD(dst, ii) do { const int t_ = (tid + 512 * (ii)) >> 7, tl_ = t0 + t_, pos_ = tl_ % L; \
;             _Pragma("unroll") for (int tap = 0; tap < 5; ++tap) { const int pp = pos_ + tap - 2; \
;                 dst[tap] = (pp >= 0 && pp < L) ? *(const u32x4*)(p + (size_t)(tl_ + tap - 2) * DINP + PC_XBC + c0) : (u32x4){0u, 0u, 0u, 0u}; } } while (0)
; __device__ __forceinline__ void prep_tile64(LAS unsigned char* lds, const Params& P, const MixBufs& B, const bf16_t* sw, int layer, int L, int tile) {
;     ...
; #pragma unroll 1
;         for (int i = 0; i < 16; ++i) {
; #pragma unroll
;             for (int tap = 0; tap < 5; ++tap) xr[tap] = xn[tap];
;             if (i < 15) CONV_LOAD(xn, i + 1);
;             float acc[8];
; #pragma unroll
;             for (int j = 0; j < 8; ++j) acc[j] = bs[j];
; #pragma unroll
;             for (int tap = 0; tap < 5; ++tap) { float x[8]; unpack8(xr[tap], x);
; #pragma unroll
;                 for (int j = 0; j < 8; ++j) acc[j] += wt[tap][j] * x[j]; }
;             const int tl = t0 + ((tid + 512 * i) >> 7);
;             u32x4 o; o.x = pk2(silu(acc[0]), silu(acc[1])); o.y = pk2(silu(acc[2]), silu(acc[3])); o.z = pk2(silu(acc[4]), silu(acc[5])); o.w = pk2(silu(acc[6]), silu(acc[7]));
;             *(u32x4*)(B.ssd_x + (size_t)tl * 1024 + c0) = o;
;         }
.Lconv_loop:
	global_load_dwordx4 v[76:79], v[54:55], off offset:832
	v_lshl_add_u64 v[54:55], v[54:55], 0, s[6:7]
	v_lshlrev_b32_e32 v88, 16, v56
	v_and_b32_e32 v89, 0xffff0000, v56
	v_lshlrev_b32_e32 v90, 16, v57
	v_and_b32_e32 v91, 0xffff0000, v57
	v_pk_fma_f32 v[80:81], v[16:17], v[88:89], v[8:9]
	v_pk_fma_f32 v[82:83], v[18:19], v[90:91], v[10:11]
	v_lshlrev_b32_e32 v88, 16, v58
	v_and_b32_e32 v89, 0xffff0000, v58
	v_lshlrev_b32_e32 v90, 16, v59
	v_and_b32_e32 v91, 0xffff0000, v59
	v_pk_fma_f32 v[84:85], v[12:13], v[88:89], v[4:5]
	v_pk_fma_f32 v[86:87], v[14:15], v[90:91], v[6:7]
	v_lshlrev_b32_e32 v88, 16, v60
	v_and_b32_e32 v89, 0xffff0000, v60
	v_lshlrev_b32_e32 v90, 16, v61
	v_and_b32_e32 v91, 0xffff0000, v61
	v_pk_fma_f32 v[80:81], v[20:21], v[88:89], v[80:81]
	v_pk_fma_f32 v[82:83], v[22:23], v[90:91], v[82:83]
	v_lshlrev_b32_e32 v88, 16, v62
	v_and_b32_e32 v89, 0xffff0000, v62
	v_lshlrev_b32_e32 v90, 16, v63
	v_and_b32_e32 v91, 0xffff0000, v63
	v_pk_fma_f32 v[84:85], v[24:25], v[88:89], v[84:85]
	v_pk_fma_f32 v[86:87], v[26:27], v[90:91], v[86:87]
	v_lshlrev_b32_e32 v88, 16, v64
	v_and_b32_e32 v89, 0xffff0000, v64
	v_lshlrev_b32_e32 v90, 16, v65
	v_and_b32_e32 v91, 0xffff0000, v65
	v_pk_fma_f32 v[80:81], v[28:29], v[88:89], v[80:81]
	v_pk_fma_f32 v[82:83], v[30:31], v[90:91], v[82:83]
	v_lshlrev_b32_e32 v88, 16, v66
	v_and_b32_e32 v89, 0xffff0000, v66
	v_lshlrev_b32_e32 v90, 16, v67
	v_and_b32_e32 v91, 0xffff0000, v67
	v_pk_fma_f32 v[84:85], v[32:33], v[88:89], v[84:85]
	v_pk_fma_f32 v[86:87], v[34:35], v[90:91], v[86:87]
	v_lshlrev_b32_e32 v88, 16, v68
	v_and_b32_e32 v89, 0xffff0000, v68
	v_lshlrev_b32_e32 v90, 16, v69
	v_and_b32_e32 v91, 0xffff0000, v69
	v_pk_fma_f32 v[80:81], v[36:37], v[88:89], v[80:81]
	v_pk_fma_f32 v[82:83], v[38:39], v[90:91], v[82:83]
	v_lshlrev_b32_e32 v88, 16, v70
	v_and_b32_e32 v89, 0xffff0000, v70
	v_lshlrev_b32_e32 v90, 16, v71
	v_and_b32_e32 v91, 0xffff0000, v71
	v_pk_fma_f32 v[84:85], v[40:41], v[88:89], v[84:85]
	v_pk_fma_f32 v[86:87], v[42:43], v[90:91], v[86:87]
	v_lshlrev_b32_e32 v88, 16, v72
	v_and_b32_e32 v89, 0xffff0000, v72
	v_lshlrev_b32_e32 v90, 16, v73
	v_and_b32_e32 v91, 0xffff0000, v73
	v_pk_fma_f32 v[80:81], v[44:45], v[88:89], v[80:81]
	v_pk_fma_f32 v[82:83], v[46:47], v[90:91], v[82:83]
	v_lshlrev_b32_e32 v88, 16, v74
	v_and_b32_e32 v89, 0xffff0000, v74
	v_lshlrev_b32_e32 v90, 16, v75
	v_and_b32_e32 v91, 0xffff0000, v75
	v_pk_fma_f32 v[84:85], v[48:49], v[88:89], v[84:85]
	v_pk_fma_f32 v[86:87], v[50:51], v[90:91], v[86:87]
	v_mul_f32_e32 v88, 0xbfb8aa3b, v80
	v_mul_f32_e32 v89, 0xbfb8aa3b, v81
	v_mul_f32_e32 v90, 0xbfb8aa3b, v82
	v_mul_f32_e32 v91, 0xbfb8aa3b, v83
	v_exp_f32_e32 v88, v88
	v_exp_f32_e32 v89, v89
	v_exp_f32_e32 v90, v90
	v_exp_f32_e32 v91, v91
	v_add_f32_e32 v88, 1.0, v88
	v_add_f32_e32 v89, 1.0, v89
	v_add_f32_e32 v90, 1.0, v90
	v_add_f32_e32 v91, 1.0, v91
	v_rcp_f32_e32 v88, v88
	v_rcp_f32_e32 v89, v89
	v_rcp_f32_e32 v90, v90
	v_rcp_f32_e32 v91, v91
	s_nop 0
	v_pk_mul_f32 v[80:81], v[80:81], v[88:89]
	v_pk_mul_f32 v[82:83], v[82:83], v[90:91]
	v_cvt_pk_bf16_f32 v96, v80, v81
	v_cvt_pk_bf16_f32 v97, v82, v83
	v_mul_f32_e32 v88, 0xbfb8aa3b, v84
	v_mul_f32_e32 v89, 0xbfb8aa3b, v85
	v_mul_f32_e32 v90, 0xbfb8aa3b, v86
	v_mul_f32_e32 v91, 0xbfb8aa3b, v87
	v_exp_f32_e32 v88, v88
	v_exp_f32_e32 v89, v89
	v_exp_f32_e32 v90, v90
	v_exp_f32_e32 v91, v91
	v_add_f32_e32 v88, 1.0, v88
	v_add_f32_e32 v89, 1.0, v89
	v_add_f32_e32 v90, 1.0, v90
	v_add_f32_e32 v91, 1.0, v91
	v_rcp_f32_e32 v88, v88
	v_rcp_f32_e32 v89, v89
	v_rcp_f32_e32 v90, v90
	v_rcp_f32_e32 v91, v91
	s_nop 0
	v_pk_mul_f32 v[84:85], v[84:85], v[88:89]
	v_pk_mul_f32 v[86:87], v[86:87], v[90:91]
	v_cvt_pk_bf16_f32 v98, v84, v85
	v_cvt_pk_bf16_f32 v99, v86, v87
	global_store_dwordx4 v[94:95], v[96:99], off
	v_lshl_add_u64 v[94:95], v[94:95], 0, s[0:1]
	v_cmp_gt_u32_e32 vcc, v0, v2
	v_add_u32_e32 v0, 1, v0
	s_waitcnt vmcnt(1)
	v_cndmask_b32_e32 v76, v76, v1, vcc
	v_cndmask_b32_e32 v77, v77, v1, vcc
	v_cndmask_b32_e32 v78, v78, v1, vcc
	v_cndmask_b32_e32 v79, v79, v1, vcc
	v_mov_b64_e32 v[56:57], v[60:61]
	v_mov_b64_e32 v[58:59], v[62:63]
	v_mov_b64_e32 v[60:61], v[64:65]
	v_mov_b64_e32 v[62:63], v[66:67]
	v_mov_b64_e32 v[64:65], v[68:69]
	v_mov_b64_e32 v[66:67], v[70:71]
	v_mov_b64_e32 v[68:69], v[72:73]
	v_mov_b64_e32 v[70:71], v[74:75]
	v_mov_b64_e32 v[72:73], v[76:77]
	v_mov_b64_e32 v[74:75], v[78:79]
	s_add_i32 s5, s5, 1
	s_cmp_lg_u32 s5, 16
	s_cbranch_scc1 .Lconv_loop
	s_waitcnt vmcnt(0)
	s_branch .LBB0_223
